# v14 plus fox sample-unit F cumsum loads batched (wave 0 issues its 17 loads per lane together)
# baseline (speedup 1.0000x reference)
; template <int BR>
; __device__ __forceinline__ void sample_unit(const SampP& P, int bs, int h, char* lds, float lam) {
;     ...
;   if (BR == 1) {
;     if (wid == 0) {
;       float loc[17]; float s = 0.f;
; #pragma unroll
;       for (int i = 0; i < 17; ++i) { const int j = lane * 17 + i; float v = 0.f;
;         if (j < PAST) v = P.clogf[((size_t)bs * PAST + j) * 8 + h]; else if (j < PAST + 16) v = P.logf[(qrow + (j - PAST)) * 8 + h];
;         s += v; loc[i] = s; }
.LBB0_411:
	s_bfe_u32 s91, s33, 0x50003
	s_lshl_b32 s90, s91, 4
	s_and_b32 s92, s33, 7
	s_bitset1_b32 s90, 14
	s_lshr_b32 s94, s33, 3
	s_and_b32 s0, s33, 0x100
	s_lshl_b32 s89, s92, 7
	s_lshl_b32 s93, s90, 10
	v_or_b32_e32 v2, s90, v50
	s_cmp_lg_u32 s0, 0
	v_lshlrev_b32_e32 v82, 11, v2
	v_mov_b32_e32 v83, v53
	s_mov_b64 s[0:1], -1
	v_lshlrev_b32_e32 v80, 1, v54
	s_cbranch_scc0 .LBB0_638
	v_lshl_add_u64 v[2:3], s[64:65], 0, v[82:83]
	s_lshl_b32 s14, s89, 1
	v_lshl_add_u64 v[2:3], v[2:3], 0, s[14:15]
	v_mov_b32_e32 v81, v53
	v_lshl_add_u64 v[14:15], v[2:3], 0, v[80:81]
	global_load_dwordx4 v[2:5], v[14:15], off
	global_load_dwordx4 v[6:9], v[14:15], off offset:64
	global_load_dwordx4 v[10:13], v[14:15], off offset:128
	s_nop 0
	global_load_dwordx4 v[14:17], v[14:15], off offset:192
	s_waitcnt vmcnt(63) expcnt(7) lgkmcnt(15)
	s_barrier
	s_mov_b64 s[0:1], exec
	v_readlane_b32 s2, v250, 20
	v_readlane_b32 s3, v250, 21
	s_and_b64 s[2:3], s[0:1], s[2:3]
	s_mov_b64 exec, s[2:3]
	s_cbranch_execz .LBB0_515
	s_mov_b64 exec, -1
	v_and_b32_e32 v37, 63, v1
	v_readlane_b32 s2, v251, 15
	v_readlane_b32 s3, v251, 16
	v_readlane_b32 s4, v251, 26
	v_readlane_b32 s5, v251, 27
	v_mul_u32_u24_e32 v35, 0x220, v37
	v_add_u32_e32 v36, 0xffff8080, v35
	v_mul_u32_u24_e32 v42, 68, v37
	v_add_u32_e32 v42, 0x21000, v42
	v_mov_b32_e32 v18, 0
	v_mov_b32_e32 v19, 0
	v_mov_b32_e32 v20, 0
	v_mov_b32_e32 v21, 0
	v_mov_b32_e32 v22, 0
	v_mov_b32_e32 v23, 0
	v_mov_b32_e32 v24, 0
	v_mov_b32_e32 v25, 0
	v_mov_b32_e32 v26, 0
	v_mov_b32_e32 v27, 0
	v_mov_b32_e32 v28, 0
	v_mov_b32_e32 v29, 0
	v_mov_b32_e32 v30, 0
	v_mov_b32_e32 v31, 0
	v_mov_b32_e32 v32, 0
	v_mov_b32_e32 v33, 0
	v_mov_b32_e32 v34, 0
	s_lshl_b32 s8, s91, 15
	s_add_u32 s2, s2, s8
	s_addc_u32 s3, s3, 0
	s_lshl_b32 s8, s92, 2
	s_add_u32 s2, s2, s8
	s_addc_u32 s3, s3, 0
	s_add_u32 s4, s4, 0x2257ff80
	s_addc_u32 s5, s5, 0
	s_lshl_b32 s9, s91, 9
	s_add_u32 s4, s4, s9
	s_addc_u32 s5, s5, 0
	s_add_u32 s4, s4, s8
	s_addc_u32 s5, s5, 0
	s_mov_b32 exec_lo, -1
	s_mov_b32 exec_hi, 0x1fffffff
	global_load_dword v18, v35, s[2:3] offset:0
	s_mov_b32 exec_lo, 0
	s_mov_b32 exec_hi, 0x20000000
	global_load_dword v18, v36, s[4:5] offset:0
	s_mov_b32 exec_lo, -1
	s_mov_b32 exec_hi, 0x1fffffff
	global_load_dword v19, v35, s[2:3] offset:32
	s_mov_b32 exec_lo, 0
	s_mov_b32 exec_hi, 0x20000000
	global_load_dword v19, v36, s[4:5] offset:32
	s_mov_b32 exec_lo, -1
	s_mov_b32 exec_hi, 0x1fffffff
	global_load_dword v20, v35, s[2:3] offset:64
	s_mov_b32 exec_lo, 0
	s_mov_b32 exec_hi, 0x20000000
	global_load_dword v20, v36, s[4:5] offset:64
	s_mov_b32 exec_lo, -1
	s_mov_b32 exec_hi, 0x1fffffff
	global_load_dword v21, v35, s[2:3] offset:96
	s_mov_b32 exec_lo, -1
	s_mov_b32 exec_hi, 0xfffffff
	global_load_dword v22, v35, s[2:3] offset:128
	s_mov_b32 exec_lo, 0
	s_mov_b32 exec_hi, 0x10000000
	global_load_dword v22, v36, s[4:5] offset:128
	s_mov_b32 exec_lo, -1
	s_mov_b32 exec_hi, 0xfffffff
	global_load_dword v23, v35, s[2:3] offset:160
	s_mov_b32 exec_lo, 0
	s_mov_b32 exec_hi, 0x10000000
	global_load_dword v23, v36, s[4:5] offset:160
	s_mov_b32 exec_lo, -1
	s_mov_b32 exec_hi, 0xfffffff
	global_load_dword v24, v35, s[2:3] offset:192
	s_mov_b32 exec_lo, 0
	s_mov_b32 exec_hi, 0x10000000
	global_load_dword v24, v36, s[4:5] offset:192
	s_mov_b32 exec_lo, -1
	s_mov_b32 exec_hi, 0xfffffff
	global_load_dword v25, v35, s[2:3] offset:224
	s_mov_b32 exec_lo, 0
	s_mov_b32 exec_hi, 0x10000000
	global_load_dword v25, v36, s[4:5] offset:224
	s_mov_b32 exec_lo, -1
	s_mov_b32 exec_hi, 0xfffffff
	global_load_dword v26, v35, s[2:3] offset:256
	s_mov_b32 exec_lo, 0
	s_mov_b32 exec_hi, 0x10000000
	global_load_dword v26, v36, s[4:5] offset:256
	s_mov_b32 exec_lo, -1
	s_mov_b32 exec_hi, 0xfffffff
	global_load_dword v27, v35, s[2:3] offset:288
	s_mov_b32 exec_lo, 0
	s_mov_b32 exec_hi, 0x10000000
	global_load_dword v27, v36, s[4:5] offset:288
	s_mov_b32 exec_lo, -1
	s_mov_b32 exec_hi, 0xfffffff
	global_load_dword v28, v35, s[2:3] offset:320
	s_mov_b32 exec_lo, 0
	s_mov_b32 exec_hi, 0x10000000
	global_load_dword v28, v36, s[4:5] offset:320
	s_mov_b32 exec_lo, -1
	s_mov_b32 exec_hi, 0xfffffff
	global_load_dword v29, v35, s[2:3] offset:352
	s_mov_b32 exec_lo, 0
	s_mov_b32 exec_hi, 0x10000000
	global_load_dword v29, v36, s[4:5] offset:352
	s_mov_b32 exec_lo, -1
	s_mov_b32 exec_hi, 0xfffffff
	global_load_dword v30, v35, s[2:3] offset:384
	s_mov_b32 exec_lo, 0
	s_mov_b32 exec_hi, 0x10000000
	global_load_dword v30, v36, s[4:5] offset:384
	s_mov_b32 exec_lo, -1
	s_mov_b32 exec_hi, 0xfffffff
	global_load_dword v31, v35, s[2:3] offset:416
	s_mov_b32 exec_lo, 0
	s_mov_b32 exec_hi, 0x10000000
	global_load_dword v31, v36, s[4:5] offset:416
	s_mov_b32 exec_lo, -1
	s_mov_b32 exec_hi, 0xfffffff
	global_load_dword v32, v35, s[2:3] offset:448
	s_mov_b32 exec_lo, 0
	s_mov_b32 exec_hi, 0x10000000
	global_load_dword v32, v36, s[4:5] offset:448
	s_mov_b32 exec_lo, -1
	s_mov_b32 exec_hi, 0xfffffff
	global_load_dword v33, v35, s[2:3] offset:480
	s_mov_b32 exec_lo, 0
	s_mov_b32 exec_hi, 0x10000000
	global_load_dword v33, v36, s[4:5] offset:480
	s_mov_b32 exec_lo, -1
	s_mov_b32 exec_hi, 0xfffffff
	global_load_dword v34, v35, s[2:3] offset:512
	s_mov_b32 exec_lo, 0
	s_mov_b32 exec_hi, 0x10000000
	global_load_dword v34, v36, s[4:5] offset:512
	s_mov_b64 exec, -1
	s_waitcnt vmcnt(0)
; template <int BR>
; __device__ __forceinline__ void sample_unit(const SampP& P, int bs, int h, char* lds, float lam) {
;     ...
;       for (int i = 0; i < 17; ++i) { const int j = lane * 17 + i; float v = 0.f;
;         if (j < PAST) v = P.clogf[((size_t)bs * PAST + j) * 8 + h]; else if (j < PAST + 16) v = P.logf[(qrow + (j - PAST)) * 8 + h];
;         s += v; loc[i] = s; }
;       float inc = s;
; #pragma unroll
;       for (int o = 1; o < 64; o <<= 1) { const float t = __shfl_up(inc, o); if (lane >= o) inc += t; }
;       const float off = inc - s;
; #pragma unroll
;       for (int i = 0; i < 17; ++i) { const int j = lane * 17 + i; if (j < PAST + 16) Fl[j] = (off + loc[i]) * LOG2E; }
;     }
	v_add_f32_e32 v19, v18, v19
	v_add_f32_e32 v20, v19, v20
	v_add_f32_e32 v21, v20, v21
	v_add_f32_e32 v22, v21, v22
	v_add_f32_e32 v23, v22, v23
	v_add_f32_e32 v24, v23, v24
	v_add_f32_e32 v25, v24, v25
	v_add_f32_e32 v26, v25, v26
	v_add_f32_e32 v27, v26, v27
	v_add_f32_e32 v28, v27, v28
	v_add_f32_e32 v29, v28, v29
	v_add_f32_e32 v30, v29, v30
	v_add_f32_e32 v31, v30, v31
	v_add_f32_e32 v32, v31, v32
	v_add_f32_e32 v33, v32, v33
	v_add_f32_e32 v34, v33, v34
	v_mov_b32_e32 v38, v34
	v_subrev_u32_e32 v40, 1, v37
	v_max_i32_e32 v40, 0, v40
	v_lshlrev_b32_e32 v40, 2, v40
	ds_bpermute_b32 v39, v40, v38
	v_cmp_le_u32_e64 s[16:17], 1, v37
	s_waitcnt lgkmcnt(0)
	v_add_f32_e32 v39, v38, v39
	v_cndmask_b32_e64 v38, v38, v39, s[16:17]
	v_subrev_u32_e32 v40, 2, v37
	v_max_i32_e32 v40, 0, v40
	v_lshlrev_b32_e32 v40, 2, v40
	ds_bpermute_b32 v39, v40, v38
	v_cmp_le_u32_e64 s[16:17], 2, v37
	s_waitcnt lgkmcnt(0)
	v_add_f32_e32 v39, v38, v39
	v_cndmask_b32_e64 v38, v38, v39, s[16:17]
	v_subrev_u32_e32 v40, 4, v37
	v_max_i32_e32 v40, 0, v40
	v_lshlrev_b32_e32 v40, 2, v40
	ds_bpermute_b32 v39, v40, v38
	v_cmp_le_u32_e64 s[16:17], 4, v37
	s_waitcnt lgkmcnt(0)
	v_add_f32_e32 v39, v38, v39
	v_cndmask_b32_e64 v38, v38, v39, s[16:17]
	v_subrev_u32_e32 v40, 8, v37
	v_max_i32_e32 v40, 0, v40
	v_lshlrev_b32_e32 v40, 2, v40
	ds_bpermute_b32 v39, v40, v38
	v_cmp_le_u32_e64 s[16:17], 8, v37
	s_waitcnt lgkmcnt(0)
	v_add_f32_e32 v39, v38, v39
	v_cndmask_b32_e64 v38, v38, v39, s[16:17]
	v_subrev_u32_e32 v40, 16, v37
	v_max_i32_e32 v40, 0, v40
	v_lshlrev_b32_e32 v40, 2, v40
	ds_bpermute_b32 v39, v40, v38
	v_cmp_le_u32_e64 s[16:17], 16, v37
	s_waitcnt lgkmcnt(0)
	v_add_f32_e32 v39, v38, v39
	v_cndmask_b32_e64 v38, v38, v39, s[16:17]
	v_subrev_u32_e32 v40, 32, v37
	v_max_i32_e32 v40, 0, v40
	v_lshlrev_b32_e32 v40, 2, v40
	ds_bpermute_b32 v39, v40, v38
	v_cmp_le_u32_e64 s[16:17], 32, v37
	s_waitcnt lgkmcnt(0)
	v_add_f32_e32 v39, v38, v39
	v_cndmask_b32_e64 v38, v38, v39, s[16:17]
	v_sub_f32_e32 v41, v38, v34
	v_add_f32_e32 v18, v18, v41
	v_mul_f32_e32 v18, 0x3fb8aa3b, v18
	v_add_f32_e32 v19, v19, v41
	v_mul_f32_e32 v19, 0x3fb8aa3b, v19
	v_add_f32_e32 v20, v20, v41
	v_mul_f32_e32 v20, 0x3fb8aa3b, v20
	v_add_f32_e32 v21, v21, v41
	v_mul_f32_e32 v21, 0x3fb8aa3b, v21
	v_add_f32_e32 v22, v22, v41
	v_mul_f32_e32 v22, 0x3fb8aa3b, v22
	v_add_f32_e32 v23, v23, v41
	v_mul_f32_e32 v23, 0x3fb8aa3b, v23
	v_add_f32_e32 v24, v24, v41
	v_mul_f32_e32 v24, 0x3fb8aa3b, v24
	v_add_f32_e32 v25, v25, v41
	v_mul_f32_e32 v25, 0x3fb8aa3b, v25
	v_add_f32_e32 v26, v26, v41
	v_mul_f32_e32 v26, 0x3fb8aa3b, v26
	v_add_f32_e32 v27, v27, v41
	v_mul_f32_e32 v27, 0x3fb8aa3b, v27
	v_add_f32_e32 v28, v28, v41
	v_mul_f32_e32 v28, 0x3fb8aa3b, v28
	v_add_f32_e32 v29, v29, v41
	v_mul_f32_e32 v29, 0x3fb8aa3b, v29
	v_add_f32_e32 v30, v30, v41
	v_mul_f32_e32 v30, 0x3fb8aa3b, v30
	v_add_f32_e32 v31, v31, v41
	v_mul_f32_e32 v31, 0x3fb8aa3b, v31
	v_add_f32_e32 v32, v32, v41
	v_mul_f32_e32 v32, 0x3fb8aa3b, v32
	v_add_f32_e32 v33, v33, v41
	v_mul_f32_e32 v33, 0x3fb8aa3b, v33
	v_add_f32_e32 v34, v34, v41
	v_mul_f32_e32 v34, 0x3fb8aa3b, v34
	s_mov_b32 exec_lo, -1
	s_mov_b32 exec_hi, 0x3fffffff
	ds_write_b32 v42, v18 offset:0
	ds_write_b32 v42, v19 offset:4
	ds_write_b32 v42, v20 offset:8
	s_mov_b32 exec_lo, -1
	s_mov_b32 exec_hi, 0x1fffffff
	ds_write_b32 v42, v21 offset:12
	ds_write_b32 v42, v22 offset:16
	ds_write_b32 v42, v23 offset:20
	ds_write_b32 v42, v24 offset:24
	ds_write_b32 v42, v25 offset:28
	ds_write_b32 v42, v26 offset:32
	ds_write_b32 v42, v27 offset:36
	ds_write_b32 v42, v28 offset:40
	ds_write_b32 v42, v29 offset:44
	ds_write_b32 v42, v30 offset:48
	ds_write_b32 v42, v31 offset:52
	ds_write_b32 v42, v32 offset:56
	ds_write_b32 v42, v33 offset:60
	ds_write_b32 v42, v34 offset:64
	s_mov_b64 exec, -1
